# DF late half: priority raised for its MFMA burst (P.V + QK^T) only
# baseline (speedup 1.0000x reference)
.LBB0_408:
	s_andn2_b64 vcc, exec, s[10:11]
	s_cbranch_vccnz .LBB0_410
	s_lshl_b32 s10, s24, 14
	s_addk_i32 s10, 0xc000
	s_cmp_gt_i32 s24, 0
	s_cselect_b32 s10, s10, 0x10000
	v_add_u32_e32 v203, s10, v221
	s_nop 4
	ds_read_b64_tr_b16 v[80:81], v203
	ds_read_b64_tr_b16 v[82:83], v203 offset:512
	ds_read_b64_tr_b16 v[84:85], v203 offset:1024
	ds_read_b64_tr_b16 v[86:87], v203 offset:1536
	ds_read_b64_tr_b16 v[88:89], v203 offset:4096
	ds_read_b64_tr_b16 v[90:91], v203 offset:4608
	ds_read_b64_tr_b16 v[92:93], v203 offset:5120
	ds_read_b64_tr_b16 v[94:95], v203 offset:5632
	ds_read_b64_tr_b16 v[96:97], v203 offset:2048
	ds_read_b64_tr_b16 v[98:99], v203 offset:2560
	ds_read_b64_tr_b16 v[100:101], v203 offset:3072
	ds_read_b64_tr_b16 v[102:103], v203 offset:3584
	ds_read_b64_tr_b16 v[104:105], v203 offset:6144
	ds_read_b64_tr_b16 v[106:107], v203 offset:6656
	ds_read_b64_tr_b16 v[108:109], v203 offset:7168
	ds_read_b64_tr_b16 v[110:111], v203 offset:7680
	ds_read_b128 v[204:207], v202
	ds_read_b128 v[208:211], v202 offset:4096
	ds_read_b128 v[212:215], v15
	ds_read_b128 v[238:241], v15 offset:4096
	ds_read_b128 v[242:245], v14
	v_mov_b32_e32 v202, v246
	ds_read_b128 v[246:249], v14 offset:4096
	ds_read_b128 v[250:253], v0
	ds_read_b128 v[148:151], v0 offset:4096
	s_setprio 1
	s_waitcnt lgkmcnt(14)
	v_mfma_f32_32x32x16_bf16 v[64:79], v[80:83], v[144:147], v[64:79]
	v_mfma_f32_32x32x16_bf16 v[48:63], v[88:91], v[144:147], v[48:63]
	v_mfma_f32_32x32x16_bf16 v[64:79], v[84:87], v[10:13], v[64:79]
	v_mfma_f32_32x32x16_bf16 v[48:63], v[92:95], v[10:13], v[48:63]
	v_mfma_f32_32x32x16_bf16 v[64:79], v[96:99], v[6:9], v[64:79]
	s_waitcnt lgkmcnt(10)
	v_mfma_f32_32x32x16_bf16 v[48:63], v[104:107], v[6:9], v[48:63]
	v_mfma_f32_32x32x16_bf16 v[64:79], v[100:103], v[2:5], v[64:79]
	s_waitcnt lgkmcnt(8)
	v_mfma_f32_32x32x16_bf16 v[48:63], v[108:111], v[2:5], v[48:63]
	ds_read_b64_tr_b16 v[80:81], v203 offset:8192
	ds_read_b64_tr_b16 v[82:83], v203 offset:8704
	ds_read_b64_tr_b16 v[84:85], v203 offset:12288
	ds_read_b64_tr_b16 v[86:87], v203 offset:12800
	ds_read_b64_tr_b16 v[88:89], v203 offset:9216
	ds_read_b64_tr_b16 v[90:91], v203 offset:9728
	ds_read_b64_tr_b16 v[92:93], v203 offset:13312
	ds_read_b64_tr_b16 v[94:95], v203 offset:13824
	ds_read_b64_tr_b16 v[96:97], v203 offset:10240
	ds_read_b64_tr_b16 v[98:99], v203 offset:10752
	ds_read_b64_tr_b16 v[100:101], v203 offset:14336
	ds_read_b64_tr_b16 v[102:103], v203 offset:14848
	ds_read_b64_tr_b16 v[104:105], v203 offset:11264
	ds_read_b64_tr_b16 v[106:107], v203 offset:11776
	ds_read_b64_tr_b16 v[108:109], v203 offset:15360
	ds_read_b64_tr_b16 v[110:111], v203 offset:15872
	s_waitcnt lgkmcnt(14)
	v_mfma_f32_32x32x16_bf16 v[32:47], v[80:83], v[144:147], v[32:47]
	s_waitcnt lgkmcnt(12)
	v_mfma_f32_32x32x16_bf16 v[16:31], v[84:87], v[144:147], v[16:31]
	s_waitcnt lgkmcnt(10)
	v_mfma_f32_32x32x16_bf16 v[32:47], v[88:91], v[10:13], v[32:47]
	s_waitcnt lgkmcnt(8)
	v_mfma_f32_32x32x16_bf16 v[16:31], v[92:95], v[10:13], v[16:31]
	s_waitcnt lgkmcnt(6)
	v_mfma_f32_32x32x16_bf16 v[32:47], v[96:99], v[6:9], v[32:47]
	s_waitcnt lgkmcnt(4)
	v_mfma_f32_32x32x16_bf16 v[16:31], v[100:103], v[6:9], v[16:31]
	s_waitcnt lgkmcnt(2)
	v_mfma_f32_32x32x16_bf16 v[32:47], v[104:107], v[2:5], v[32:47]
	s_waitcnt lgkmcnt(0)
	v_mfma_f32_32x32x16_bf16 v[16:31], v[108:111], v[2:5], v[16:31]
	v_mfma_f32_32x32x16_bf16 v[96:111], v[204:207], v[136:139], 0
	v_mfma_f32_32x32x16_bf16 v[80:95], v[208:211], v[136:139], 0
	v_mfma_f32_32x32x16_bf16 v[96:111], v[212:215], v[128:131], v[96:111]
	v_mfma_f32_32x32x16_bf16 v[80:95], v[238:241], v[128:131], v[80:95]
	v_mfma_f32_32x32x16_bf16 v[96:111], v[242:245], v[140:143], v[96:111]
	v_mfma_f32_32x32x16_bf16 v[80:95], v[246:249], v[140:143], v[80:95]
	v_mov_b32_e32 v246, v202
	v_mfma_f32_32x32x16_bf16 v[96:111], v[250:253], v[132:135], v[96:111]
	v_mfma_f32_32x32x16_bf16 v[80:95], v[148:151], v[132:135], v[80:95]
	s_setprio 0
